# x2 + GEMM loop-tail SALU into last MFMA block + attention output stores widened to dwordx4 via v_permlane32_swap + MoBA PV transposed-V reads double-buffered (counted lgkmcnt)
# speedup vs baseline: 1.0057x; 1.0057x over previous
.LBB0_56:
	v_mad_i64_i32 v[66:67], s[10:11], s15, v188, 0
	v_ashrrev_i32_e32 v64, 3, v189
	v_lshl_add_u64 v[66:67], v[66:67], 1, s[52:53]
	s_lshl_b32 s92, s73, 1
	v_and_b32_e32 v68, -4, v64
	v_lshl_add_u64 v[66:67], v[66:67], 0, s[92:93]
	v_ashrrev_i32_e32 v69, 31, v68
	v_lshl_add_u64 v[66:67], v[68:69], 1, v[66:67]
	v_and_b32_e32 v68, 32, v233
	v_lshrrev_b32_e32 v68, 2, v68
	v_mov_b32_e32 v69, 0
	v_lshl_add_u64 v[66:67], v[68:69], 0, v[66:67]
	v_cvt_pk_bf16_f32 v48, v48, v49
	v_cvt_pk_bf16_f32 v49, v50, v51
	v_cvt_pk_bf16_f32 v50, v52, v53
	v_cvt_pk_bf16_f32 v51, v54, v55
	v_cvt_pk_bf16_f32 v52, v56, v57
	v_cvt_pk_bf16_f32 v53, v58, v59
	v_cvt_pk_bf16_f32 v54, v60, v61
	v_cvt_pk_bf16_f32 v55, v62, v63
	s_nop 1
	v_permlane32_swap_b32_e32 v48, v50
	v_permlane32_swap_b32_e32 v49, v51
	v_permlane32_swap_b32_e32 v52, v54
	v_permlane32_swap_b32_e32 v53, v55
	global_store_dwordx4 v[66:67], v[48:51], off
	global_store_dwordx4 v[66:67], v[52:55], off offset:32
	v_cvt_pk_bf16_f32 v32, v32, v33
	v_cvt_pk_bf16_f32 v33, v34, v35
	v_cvt_pk_bf16_f32 v34, v36, v37
	v_cvt_pk_bf16_f32 v35, v38, v39
	v_cvt_pk_bf16_f32 v36, v40, v41
	v_cvt_pk_bf16_f32 v37, v42, v43
	v_cvt_pk_bf16_f32 v38, v44, v45
	v_cvt_pk_bf16_f32 v39, v46, v47
	s_nop 1
	v_permlane32_swap_b32_e32 v32, v34
	v_permlane32_swap_b32_e32 v33, v35
	v_permlane32_swap_b32_e32 v36, v38
	v_permlane32_swap_b32_e32 v37, v39
	global_store_dwordx4 v[66:67], v[32:35], off offset:64
	global_store_dwordx4 v[66:67], v[36:39], off offset:96
	v_cvt_pk_bf16_f32 v16, v16, v17
	v_cvt_pk_bf16_f32 v17, v18, v19
	v_cvt_pk_bf16_f32 v18, v20, v21
	v_cvt_pk_bf16_f32 v19, v22, v23
	v_cvt_pk_bf16_f32 v20, v24, v25
	v_cvt_pk_bf16_f32 v21, v26, v27
	v_cvt_pk_bf16_f32 v22, v28, v29
	v_cvt_pk_bf16_f32 v23, v30, v31
	s_nop 1
	v_permlane32_swap_b32_e32 v16, v18
	v_permlane32_swap_b32_e32 v17, v19
	v_permlane32_swap_b32_e32 v20, v22
	v_permlane32_swap_b32_e32 v21, v23
	global_store_dwordx4 v[66:67], v[16:19], off offset:128
	global_store_dwordx4 v[66:67], v[20:23], off offset:160
	v_cvt_pk_bf16_f32 v0, v0, v1
	v_cvt_pk_bf16_f32 v1, v2, v3
	v_cvt_pk_bf16_f32 v2, v4, v5
	v_cvt_pk_bf16_f32 v3, v6, v7
	v_cvt_pk_bf16_f32 v4, v8, v9
	v_cvt_pk_bf16_f32 v5, v10, v11
	v_cvt_pk_bf16_f32 v6, v12, v13
	v_cvt_pk_bf16_f32 v7, v14, v15
	s_nop 1
	v_permlane32_swap_b32_e32 v0, v2
	v_permlane32_swap_b32_e32 v1, v3
	v_permlane32_swap_b32_e32 v4, v6
	v_permlane32_swap_b32_e32 v5, v7
	global_store_dwordx4 v[66:67], v[0:3], off offset:192
	global_store_dwordx4 v[66:67], v[4:7], off offset:224
	s_mov_b64 s[10:11], 0
	v_readlane_b32 s91, v254, 63
	s_mov_b32 s55, s17

.LBB0_141:
	v_exp_f32_e32 v64, v66
	s_nop 7
	v_exp_f32_e32 v96, v67
	v_exp_f32_e32 v97, v68
	v_exp_f32_e32 v98, v69
	v_exp_f32_e32 v99, v70
	v_cvt_pk_bf16_f32 v66, v64, v96
	v_add_f32_e32 v64, 0, v64
	v_exp_f32_e32 v100, v71
	v_add_f32_e32 v64, v96, v64
	v_exp_f32_e32 v101, v72
	v_add_f32_e32 v64, v97, v64
	v_exp_f32_e32 v102, v73
	v_add_f32_e32 v64, v98, v64
	v_exp_f32_e32 v74, v74
	v_add_f32_e32 v64, v99, v64
	v_exp_f32_e32 v75, v75
	v_add_f32_e32 v64, v100, v64
	v_exp_f32_e32 v106, v160
	v_exp_f32_e32 v107, v161
	v_exp_f32_e32 v76, v76
	v_add_f32_e32 v64, v101, v64
	v_exp_f32_e32 v77, v77
	v_add_f32_e32 v64, v102, v64
	v_exp_f32_e32 v108, v162
	v_exp_f32_e32 v78, v78
	v_add_f32_e32 v64, v74, v64
	v_exp_f32_e32 v109, v163
	v_exp_f32_e32 v79, v79
	v_add_f32_e32 v64, v75, v64
	v_exp_f32_e32 v110, v164
	v_cvt_pk_bf16_f32 v96, v106, v107
	v_add_f32_e32 v106, 0, v106
	v_add_f32_e32 v64, v76, v64
	v_exp_f32_e32 v111, v165
	v_add_f32_e32 v106, v107, v106
	v_exp_f32_e32 v103, v158
	v_add_f32_e32 v64, v77, v64
	v_exp_f32_e32 v158, v166
	v_add_f32_e32 v106, v108, v106
	v_exp_f32_e32 v104, v159
	v_add_f32_e32 v64, v78, v64
	v_exp_f32_e32 v159, v167
	v_add_f32_e32 v106, v109, v106
	v_cvt_pk_bf16_f32 v72, v78, v79
	v_add_f32_e32 v64, v79, v64
	v_exp_f32_e32 v78, v168
	v_exp_f32_e32 v79, v169
	v_add_f32_e32 v106, v110, v106
	v_add_f32_e32 v106, v111, v106
	v_cvt_pk_bf16_f32 v68, v99, v100
	v_exp_f32_e32 v100, v170
	v_add_f32_e32 v106, v158, v106
	v_cvt_pk_bf16_f32 v69, v101, v102
	v_exp_f32_e32 v101, v171
	v_add_f32_e32 v106, v159, v106
	v_cvt_pk_bf16_f32 v70, v74, v75
	v_exp_f32_e32 v102, v172
	v_cvt_pk_bf16_f32 v74, v78, v79
	v_add_f32_e32 v78, v78, v106
	v_cvt_pk_bf16_f32 v73, v103, v104
	v_add_f32_e32 v64, v103, v64
	v_exp_f32_e32 v103, v173
	v_add_f32_e32 v78, v79, v78
	v_add_f32_e32 v64, v104, v64
	v_exp_f32_e32 v104, v174
	v_add_f32_e32 v78, v100, v78
	v_exp_f32_e32 v105, v175
	v_add_f32_e32 v78, v101, v78
	v_add_f32_e32 v78, v102, v78
	v_add_f32_e32 v78, v103, v78
	v_add_f32_e32 v78, v104, v78
	v_add_f32_e32 v64, v202, v64
	v_add_f32_e32 v78, v105, v78
	v_add_f32_e32 v202, v64, v78
	v_add3_u32 v64, s49, v193, v195
	v_add3_u32 v64, v64, v196, v197
	v_add_u32_e32 v78, v64, v198
	v_cvt_pk_bf16_f32 v67, v97, v98
	v_cvt_pk_bf16_f32 v71, v76, v77
	v_cvt_pk_bf16_f32 v75, v100, v101
	v_cvt_pk_bf16_f32 v76, v102, v103
	v_cvt_pk_bf16_f32 v77, v104, v105
	v_cvt_pk_bf16_f32 v97, v108, v109
	v_cvt_pk_bf16_f32 v98, v110, v111
	v_cvt_pk_bf16_f32 v99, v158, v159
	v_add_u32_e32 v64, v64, v199
	s_waitcnt vmcnt(0)
	ds_read_b64_tr_b16 v[100:101], v78 offset:16384
	ds_read_b64_tr_b16 v[104:105], v78 offset:20480
	ds_read_b64_tr_b16 v[108:109], v78 offset:20992
	ds_read_b64_tr_b16 v[158:159], v78 offset:16896
	ds_read_b64_tr_b16 v[102:103], v64 offset:18432
	ds_read_b64_tr_b16 v[106:107], v64 offset:22528
	ds_read_b64_tr_b16 v[110:111], v64 offset:23040
	ds_read_b64_tr_b16 v[160:161], v64 offset:18944
	ds_read_b64_tr_b16 v[162:163], v78 offset:17408
	ds_read_b64_tr_b16 v[166:167], v78 offset:21504
	ds_read_b64_tr_b16 v[170:171], v78 offset:22016
	ds_read_b64_tr_b16 v[216:217], v78 offset:17920
	ds_read_b64_tr_b16 v[164:165], v64 offset:19456
	ds_read_b64_tr_b16 v[168:169], v64 offset:23552
	ds_read_b64_tr_b16 v[172:173], v64 offset:24064
	ds_read_b64_tr_b16 v[218:219], v64 offset:19968
	s_waitcnt lgkmcnt(8)
	v_mfma_f32_32x32x16_bf16 v[48:63], v[100:103], v[66:69], v[48:63]
	v_mfma_f32_32x32x16_bf16 v[32:47], v[158:161], v[66:69], v[32:47]
	v_mfma_f32_32x32x16_bf16 v[48:63], v[104:107], v[70:73], v[48:63]
	v_mfma_f32_32x32x16_bf16 v[32:47], v[108:111], v[70:73], v[32:47]
	ds_read_b64_tr_b16 v[100:101], v78 offset:24576
	ds_read_b64_tr_b16 v[104:105], v78 offset:28672
	ds_read_b64_tr_b16 v[108:109], v78 offset:29184
	ds_read_b64_tr_b16 v[158:159], v78 offset:25088
	ds_read_b64_tr_b16 v[102:103], v64 offset:26624
	ds_read_b64_tr_b16 v[106:107], v64 offset:30720
	ds_read_b64_tr_b16 v[110:111], v64 offset:31232
	ds_read_b64_tr_b16 v[160:161], v64 offset:27136
	s_waitcnt lgkmcnt(8)
	v_mfma_f32_32x32x16_bf16 v[16:31], v[162:165], v[66:69], v[16:31]
	v_mfma_f32_32x32x16_bf16 v[0:15], v[216:219], v[66:69], v[0:15]
	v_mfma_f32_32x32x16_bf16 v[16:31], v[166:169], v[70:73], v[16:31]
	v_mfma_f32_32x32x16_bf16 v[0:15], v[170:173], v[70:73], v[0:15]
	ds_read_b64_tr_b16 v[162:163], v78 offset:25600
	ds_read_b64_tr_b16 v[166:167], v78 offset:29696
	ds_read_b64_tr_b16 v[170:171], v78 offset:30208
	ds_read_b64_tr_b16 v[216:217], v78 offset:26112
	ds_read_b64_tr_b16 v[164:165], v64 offset:27648
	ds_read_b64_tr_b16 v[168:169], v64 offset:31744
	ds_read_b64_tr_b16 v[172:173], v64 offset:32256
	ds_read_b64_tr_b16 v[218:219], v64 offset:28160
	s_waitcnt lgkmcnt(8)
	v_mfma_f32_32x32x16_bf16 v[48:63], v[100:103], v[96:99], v[48:63]
	v_mfma_f32_32x32x16_bf16 v[32:47], v[158:161], v[96:99], v[32:47]
	v_mfma_f32_32x32x16_bf16 v[48:63], v[104:107], v[74:77], v[48:63]
	v_mfma_f32_32x32x16_bf16 v[32:47], v[108:111], v[74:77], v[32:47]
	s_waitcnt lgkmcnt(0)
	v_mfma_f32_32x32x16_bf16 v[16:31], v[162:165], v[96:99], v[16:31]
	v_mfma_f32_32x32x16_bf16 v[0:15], v[216:219], v[96:99], v[0:15]
	v_mfma_f32_32x32x16_bf16 v[16:31], v[166:169], v[74:77], v[16:31]
	v_mfma_f32_32x32x16_bf16 v[0:15], v[170:173], v[74:77], v[0:15]
	s_and_b64 vcc, exec, s[20:21]
	s_mov_b64 s[10:11], -1
	s_cbranch_vccz .LBB0_126

.LBB0_145:
	ds_bpermute_b32 v64, v188, v202
	s_waitcnt lgkmcnt(0)
	v_add_f32_e32 v64, v202, v64
	v_div_scale_f32 v66, s[10:11], v64, v64, 1.0
	v_rcp_f32_e32 v67, v66
	s_nop 0
	v_fma_f32 v68, -v66, v67, 1.0
	v_fmac_f32_e32 v67, v68, v67
	v_div_scale_f32 v68, vcc, 1.0, v64, 1.0
	v_mul_f32_e32 v69, v68, v67
	v_fma_f32 v70, -v66, v69, v68
	v_fmac_f32_e32 v69, v70, v67
	v_fma_f32 v66, -v66, v69, v68
	v_div_fmas_f32 v66, v66, v67, v69
	v_div_fixup_f32 v64, v66, v64, 1.0
	v_mad_i64_i32 v[66:67], s[10:11], s15, v157, 0
	v_ashrrev_i32_e32 v68, 3, v144
	v_lshl_add_u64 v[66:67], v[66:67], 1, s[52:53]
	v_and_b32_e32 v68, -4, v68
	v_lshl_add_u64 v[66:67], s[92:93], 1, v[66:67]
	v_ashrrev_i32_e32 v69, 31, v68
	v_lshl_add_u64 v[66:67], v[68:69], 1, v[66:67]
	v_and_b32_e32 v68, 32, v233
	v_lshrrev_b32_e32 v68, 2, v68
	v_mov_b32_e32 v69, 0
	v_lshl_add_u64 v[66:67], v[68:69], 0, v[66:67]
	v_pk_mul_f32 v[48:49], v[48:49], v[64:65] op_sel_hi:[1,0]
	v_pk_mul_f32 v[50:51], v[50:51], v[64:65] op_sel_hi:[1,0]
	v_pk_mul_f32 v[52:53], v[52:53], v[64:65] op_sel_hi:[1,0]
	v_pk_mul_f32 v[54:55], v[54:55], v[64:65] op_sel_hi:[1,0]
	v_pk_mul_f32 v[56:57], v[56:57], v[64:65] op_sel_hi:[1,0]
	v_pk_mul_f32 v[58:59], v[58:59], v[64:65] op_sel_hi:[1,0]
	v_pk_mul_f32 v[60:61], v[60:61], v[64:65] op_sel_hi:[1,0]
	v_pk_mul_f32 v[62:63], v[62:63], v[64:65] op_sel_hi:[1,0]
	v_cvt_pk_bf16_f32 v48, v48, v49
	v_cvt_pk_bf16_f32 v49, v50, v51
	v_cvt_pk_bf16_f32 v50, v52, v53
	v_cvt_pk_bf16_f32 v51, v54, v55
	v_cvt_pk_bf16_f32 v52, v56, v57
	v_cvt_pk_bf16_f32 v53, v58, v59
	v_cvt_pk_bf16_f32 v54, v60, v61
	v_cvt_pk_bf16_f32 v55, v62, v63
	s_nop 1
	v_permlane32_swap_b32_e32 v48, v50
	v_permlane32_swap_b32_e32 v49, v51
	v_permlane32_swap_b32_e32 v52, v54
	v_permlane32_swap_b32_e32 v53, v55
	global_store_dwordx4 v[66:67], v[48:51], off
	global_store_dwordx4 v[66:67], v[52:55], off offset:32
	v_pk_mul_f32 v[32:33], v[32:33], v[64:65] op_sel_hi:[1,0]
	v_pk_mul_f32 v[34:35], v[34:35], v[64:65] op_sel_hi:[1,0]
	v_pk_mul_f32 v[36:37], v[36:37], v[64:65] op_sel_hi:[1,0]
	v_pk_mul_f32 v[38:39], v[38:39], v[64:65] op_sel_hi:[1,0]
	v_pk_mul_f32 v[40:41], v[40:41], v[64:65] op_sel_hi:[1,0]
	v_pk_mul_f32 v[42:43], v[42:43], v[64:65] op_sel_hi:[1,0]
	v_pk_mul_f32 v[44:45], v[44:45], v[64:65] op_sel_hi:[1,0]
	v_pk_mul_f32 v[46:47], v[46:47], v[64:65] op_sel_hi:[1,0]
	v_cvt_pk_bf16_f32 v32, v32, v33
	v_cvt_pk_bf16_f32 v33, v34, v35
	v_cvt_pk_bf16_f32 v34, v36, v37
	v_cvt_pk_bf16_f32 v35, v38, v39
	v_cvt_pk_bf16_f32 v36, v40, v41
	v_cvt_pk_bf16_f32 v37, v42, v43
	v_cvt_pk_bf16_f32 v38, v44, v45
	v_cvt_pk_bf16_f32 v39, v46, v47
	s_nop 1
	v_permlane32_swap_b32_e32 v32, v34
	v_permlane32_swap_b32_e32 v33, v35
	v_permlane32_swap_b32_e32 v36, v38
	v_permlane32_swap_b32_e32 v37, v39
	global_store_dwordx4 v[66:67], v[32:35], off offset:64
	global_store_dwordx4 v[66:67], v[36:39], off offset:96
	v_pk_mul_f32 v[16:17], v[16:17], v[64:65] op_sel_hi:[1,0]
	v_pk_mul_f32 v[18:19], v[18:19], v[64:65] op_sel_hi:[1,0]
	v_pk_mul_f32 v[20:21], v[20:21], v[64:65] op_sel_hi:[1,0]
	v_pk_mul_f32 v[22:23], v[22:23], v[64:65] op_sel_hi:[1,0]
	v_pk_mul_f32 v[24:25], v[24:25], v[64:65] op_sel_hi:[1,0]
	v_pk_mul_f32 v[26:27], v[26:27], v[64:65] op_sel_hi:[1,0]
	v_pk_mul_f32 v[28:29], v[28:29], v[64:65] op_sel_hi:[1,0]
	v_pk_mul_f32 v[30:31], v[30:31], v[64:65] op_sel_hi:[1,0]
	v_cvt_pk_bf16_f32 v16, v16, v17
	v_cvt_pk_bf16_f32 v17, v18, v19
	v_cvt_pk_bf16_f32 v18, v20, v21
	v_cvt_pk_bf16_f32 v19, v22, v23
	v_cvt_pk_bf16_f32 v20, v24, v25
	v_cvt_pk_bf16_f32 v21, v26, v27
	v_cvt_pk_bf16_f32 v22, v28, v29
	v_cvt_pk_bf16_f32 v23, v30, v31
	s_nop 1
	v_permlane32_swap_b32_e32 v16, v18
	v_permlane32_swap_b32_e32 v17, v19
	v_permlane32_swap_b32_e32 v20, v22
	v_permlane32_swap_b32_e32 v21, v23
	global_store_dwordx4 v[66:67], v[16:19], off offset:128
	global_store_dwordx4 v[66:67], v[20:23], off offset:160
	v_pk_mul_f32 v[0:1], v[0:1], v[64:65] op_sel_hi:[1,0]
	v_pk_mul_f32 v[2:3], v[2:3], v[64:65] op_sel_hi:[1,0]
	v_pk_mul_f32 v[4:5], v[4:5], v[64:65] op_sel_hi:[1,0]
	v_pk_mul_f32 v[6:7], v[6:7], v[64:65] op_sel_hi:[1,0]
	v_pk_mul_f32 v[8:9], v[8:9], v[64:65] op_sel_hi:[1,0]
	v_pk_mul_f32 v[10:11], v[10:11], v[64:65] op_sel_hi:[1,0]
	v_pk_mul_f32 v[12:13], v[12:13], v[64:65] op_sel_hi:[1,0]
	v_pk_mul_f32 v[14:15], v[14:15], v[64:65] op_sel_hi:[1,0]
	v_cvt_pk_bf16_f32 v0, v0, v1
	v_cvt_pk_bf16_f32 v1, v2, v3
	v_cvt_pk_bf16_f32 v2, v4, v5
	v_cvt_pk_bf16_f32 v3, v6, v7
	v_cvt_pk_bf16_f32 v4, v8, v9
	v_cvt_pk_bf16_f32 v5, v10, v11
	v_cvt_pk_bf16_f32 v6, v12, v13
	v_cvt_pk_bf16_f32 v7, v14, v15
	s_nop 1
	v_permlane32_swap_b32_e32 v0, v2
	v_permlane32_swap_b32_e32 v1, v3
	v_permlane32_swap_b32_e32 v4, v6
	v_permlane32_swap_b32_e32 v5, v7
	global_store_dwordx4 v[66:67], v[0:3], off offset:192
	global_store_dwordx4 v[66:67], v[4:7], off offset:224

.LBB0_149:
	ds_bpermute_b32 v64, v175, v216
	s_lshl_b32 s92, s26, 1
	s_waitcnt lgkmcnt(0)
	v_add_f32_e32 v64, v216, v64
	v_div_scale_f32 v66, s[10:11], v64, v64, 1.0
	v_rcp_f32_e32 v67, v66
	s_nop 0
	v_fma_f32 v68, -v66, v67, 1.0
	v_fmac_f32_e32 v67, v68, v67
	v_div_scale_f32 v68, vcc, 1.0, v64, 1.0
	v_mul_f32_e32 v69, v68, v67
	v_fma_f32 v70, -v66, v69, v68
	v_fmac_f32_e32 v69, v70, v67
	v_fma_f32 v66, -v66, v69, v68
	v_div_fmas_f32 v66, v66, v67, v69
	v_div_fixup_f32 v64, v66, v64, 1.0
	v_mad_i64_i32 v[66:67], s[10:11], s15, v176, 0
	v_ashrrev_i32_e32 v68, 3, v174
	v_lshl_add_u64 v[66:67], v[66:67], 1, s[52:53]
	v_and_b32_e32 v68, -4, v68
	v_lshl_add_u64 v[66:67], v[66:67], 0, s[92:93]
	v_ashrrev_i32_e32 v69, 31, v68
	v_lshl_add_u64 v[66:67], v[68:69], 1, v[66:67]
	v_and_b32_e32 v68, 32, v233
	v_lshrrev_b32_e32 v68, 2, v68
	v_mov_b32_e32 v69, 0
	v_lshl_add_u64 v[66:67], v[68:69], 0, v[66:67]
	v_pk_mul_f32 v[48:49], v[48:49], v[64:65] op_sel_hi:[1,0]
	v_pk_mul_f32 v[50:51], v[50:51], v[64:65] op_sel_hi:[1,0]
	v_pk_mul_f32 v[52:53], v[52:53], v[64:65] op_sel_hi:[1,0]
	v_pk_mul_f32 v[54:55], v[54:55], v[64:65] op_sel_hi:[1,0]
	v_pk_mul_f32 v[56:57], v[56:57], v[64:65] op_sel_hi:[1,0]
	v_pk_mul_f32 v[58:59], v[58:59], v[64:65] op_sel_hi:[1,0]
	v_pk_mul_f32 v[60:61], v[60:61], v[64:65] op_sel_hi:[1,0]
	v_pk_mul_f32 v[62:63], v[62:63], v[64:65] op_sel_hi:[1,0]
	v_cvt_pk_bf16_f32 v48, v48, v49
	v_cvt_pk_bf16_f32 v49, v50, v51
	v_cvt_pk_bf16_f32 v50, v52, v53
	v_cvt_pk_bf16_f32 v51, v54, v55
	v_cvt_pk_bf16_f32 v52, v56, v57
	v_cvt_pk_bf16_f32 v53, v58, v59
	v_cvt_pk_bf16_f32 v54, v60, v61
	v_cvt_pk_bf16_f32 v55, v62, v63
	s_nop 1
	v_permlane32_swap_b32_e32 v48, v50
	v_permlane32_swap_b32_e32 v49, v51
	v_permlane32_swap_b32_e32 v52, v54
	v_permlane32_swap_b32_e32 v53, v55
	global_store_dwordx4 v[66:67], v[48:51], off offset:2560
	global_store_dwordx4 v[66:67], v[52:55], off offset:2592
	v_pk_mul_f32 v[32:33], v[32:33], v[64:65] op_sel_hi:[1,0]
	v_pk_mul_f32 v[34:35], v[34:35], v[64:65] op_sel_hi:[1,0]
	v_pk_mul_f32 v[36:37], v[36:37], v[64:65] op_sel_hi:[1,0]
	v_pk_mul_f32 v[38:39], v[38:39], v[64:65] op_sel_hi:[1,0]
	v_pk_mul_f32 v[40:41], v[40:41], v[64:65] op_sel_hi:[1,0]
	v_pk_mul_f32 v[42:43], v[42:43], v[64:65] op_sel_hi:[1,0]
	v_pk_mul_f32 v[44:45], v[44:45], v[64:65] op_sel_hi:[1,0]
	v_pk_mul_f32 v[46:47], v[46:47], v[64:65] op_sel_hi:[1,0]
	v_cvt_pk_bf16_f32 v32, v32, v33
	v_cvt_pk_bf16_f32 v33, v34, v35
	v_cvt_pk_bf16_f32 v34, v36, v37
	v_cvt_pk_bf16_f32 v35, v38, v39
	v_cvt_pk_bf16_f32 v36, v40, v41
	v_cvt_pk_bf16_f32 v37, v42, v43
	v_cvt_pk_bf16_f32 v38, v44, v45
	v_cvt_pk_bf16_f32 v39, v46, v47
	s_nop 1
	v_permlane32_swap_b32_e32 v32, v34
	v_permlane32_swap_b32_e32 v33, v35
	v_permlane32_swap_b32_e32 v36, v38
	v_permlane32_swap_b32_e32 v37, v39
	global_store_dwordx4 v[66:67], v[32:35], off offset:2624
	global_store_dwordx4 v[66:67], v[36:39], off offset:2656
	v_pk_mul_f32 v[16:17], v[16:17], v[64:65] op_sel_hi:[1,0]
	v_pk_mul_f32 v[18:19], v[18:19], v[64:65] op_sel_hi:[1,0]
	v_pk_mul_f32 v[20:21], v[20:21], v[64:65] op_sel_hi:[1,0]
	v_pk_mul_f32 v[22:23], v[22:23], v[64:65] op_sel_hi:[1,0]
	v_pk_mul_f32 v[24:25], v[24:25], v[64:65] op_sel_hi:[1,0]
	v_pk_mul_f32 v[26:27], v[26:27], v[64:65] op_sel_hi:[1,0]
	v_pk_mul_f32 v[28:29], v[28:29], v[64:65] op_sel_hi:[1,0]
	v_pk_mul_f32 v[30:31], v[30:31], v[64:65] op_sel_hi:[1,0]
	v_cvt_pk_bf16_f32 v16, v16, v17
	v_cvt_pk_bf16_f32 v17, v18, v19
	v_cvt_pk_bf16_f32 v18, v20, v21
	v_cvt_pk_bf16_f32 v19, v22, v23
	v_cvt_pk_bf16_f32 v20, v24, v25
	v_cvt_pk_bf16_f32 v21, v26, v27
	v_cvt_pk_bf16_f32 v22, v28, v29
	v_cvt_pk_bf16_f32 v23, v30, v31
	s_nop 1
	v_permlane32_swap_b32_e32 v16, v18
	v_permlane32_swap_b32_e32 v17, v19
	v_permlane32_swap_b32_e32 v20, v22
	v_permlane32_swap_b32_e32 v21, v23
	global_store_dwordx4 v[66:67], v[16:19], off offset:2688
	global_store_dwordx4 v[66:67], v[20:23], off offset:2720
	v_pk_mul_f32 v[0:1], v[0:1], v[64:65] op_sel_hi:[1,0]
	v_pk_mul_f32 v[2:3], v[2:3], v[64:65] op_sel_hi:[1,0]
	v_pk_mul_f32 v[4:5], v[4:5], v[64:65] op_sel_hi:[1,0]
	v_pk_mul_f32 v[6:7], v[6:7], v[64:65] op_sel_hi:[1,0]
	v_pk_mul_f32 v[8:9], v[8:9], v[64:65] op_sel_hi:[1,0]
	v_pk_mul_f32 v[10:11], v[10:11], v[64:65] op_sel_hi:[1,0]
	v_pk_mul_f32 v[12:13], v[12:13], v[64:65] op_sel_hi:[1,0]
	v_pk_mul_f32 v[14:15], v[14:15], v[64:65] op_sel_hi:[1,0]
	v_cvt_pk_bf16_f32 v0, v0, v1
	v_cvt_pk_bf16_f32 v1, v2, v3
	v_cvt_pk_bf16_f32 v2, v4, v5
	v_cvt_pk_bf16_f32 v3, v6, v7
	v_cvt_pk_bf16_f32 v4, v8, v9
	v_cvt_pk_bf16_f32 v5, v10, v11
	v_cvt_pk_bf16_f32 v6, v12, v13
	v_cvt_pk_bf16_f32 v7, v14, v15
	s_nop 1
	v_permlane32_swap_b32_e32 v0, v2
	v_permlane32_swap_b32_e32 v1, v3
	v_permlane32_swap_b32_e32 v4, v6
	v_permlane32_swap_b32_e32 v5, v7
	global_store_dwordx4 v[66:67], v[0:3], off offset:2752
	global_store_dwordx4 v[66:67], v[4:7], off offset:2784
	s_cbranch_execz .LBB0_97
	s_branch .LBB0_146
